# row passes: the once-read O / X row loads use the non-temporal cache policy (nt)
# baseline (speedup 1.0000x reference)
.Lxbi0_skip:
	s_barrier
	s_load_dword s0, s[2:3], 0x10
	s_load_dword s45, s[2:3], 0x0
	v_ashrrev_i32_e32 v2, 6, v0
	s_waitcnt lgkmcnt(0)
	s_lshr_b32 s0, s0, 16
	s_cmp_lg_u32 s0, 0
	s_cselect_b64 s[0:1], -1, 0
	s_cmp_lg_u64 s[0:1], 0
	s_addc_u32 s50, s45, 0
	s_lshl_b32 s51, s50, 2
	s_abs_i32 s0, s51
	v_cvt_f32_u32_e32 v1, s0
	s_sub_i32 s3, 0, s0
	s_add_i32 s1, s51, 0x27ff
	s_xor_b32 s2, s1, s51
	v_rcp_iflag_f32_e32 v1, v1
	s_abs_i32 s1, s1
	s_ashr_i32 s2, s2, 31
	v_mul_f32_e32 v1, 0x4f7ffffe, v1
	v_cvt_u32_f32_e32 v1, v1
	s_nop 0
	v_readfirstlane_b32 s4, v1
	s_mul_i32 s3, s3, s4
	s_mul_hi_u32 s3, s4, s3
	s_add_i32 s4, s4, s3
	s_mul_hi_u32 s3, s1, s4
	s_mul_i32 s4, s3, s0
	s_sub_i32 s1, s1, s4
	s_add_i32 s5, s3, 1
	s_sub_i32 s4, s1, s0
	s_cmp_ge_u32 s1, s0
	s_cselect_b32 s3, s5, s3
	s_cselect_b32 s1, s4, s1
	s_add_i32 s4, s3, 1
	s_cmp_ge_u32 s1, s0
	s_cselect_b32 s0, s4, s3
	s_xor_b32 s0, s0, s2
	s_sub_i32 s1, s0, s2
	v_readlane_b32 s0, v242, 0
	v_writelane_b32 v241, s1, 12
	s_nop 0
	v_lshl_add_u32 v1, s0, 2, v2
	v_mul_lo_u32 v16, v1, s1
	v_add_u32_e32 v1, s1, v16
	v_min_i32_e32 v40, 0x2800, v1
	v_cmp_lt_i32_e32 vcc, v16, v40
	s_and_saveexec_b64 s[0:1], vcc
	s_cbranch_execz .LBB0_218
	v_readfirstlane_b32 s6, v16
	v_readfirstlane_b32 s7, v40
	v_readlane_b32 s36, v242, 42
	v_readlane_b32 s37, v242, 43
	v_readlane_b32 s14, v242, 1
	v_readlane_b32 s15, v242, 2
	v_readlane_b32 s20, v242, 3
	v_readlane_b32 s21, v242, 4
	v_and_b32_e32 v236, 63, v137
	v_lshlrev_b32_e32 v237, 3, v236
	v_lshlrev_b32_e32 v236, 4, v236
	v_mov_b32_e32 v238, 0x358637bd
	s_sub_u32 s36, s36, 0x118
	s_subb_u32 s37, s37, 0
	s_load_dwordx2 s[12:13], s[36:37], 0x58
	s_load_dwordx4 s[16:19], s[36:37], 0x0
	s_add_u32 s22, s20, 0x2f90000
	s_addc_u32 s23, s21, 0
	s_mov_b32 s8, -1
	s_waitcnt lgkmcnt(0)
	s_cmp_lt_u32 s6, 0x2000
	s_cselect_b32 s24, s16, s18
	s_cselect_b32 s25, s17, s19
	s_cselect_b32 s9, 0, 0x2000
	s_sub_u32 s9, s6, s9
	s_lshl_b32 s9, s9, 12
	s_add_u32 s24, s24, s9
	s_addc_u32 s25, s25, 0
	global_load_dwordx4 v[188:191], v236, s[24:25] offset:0 nt
	global_load_dwordx4 v[192:195], v236, s[24:25] offset:1024 nt
	global_load_dwordx4 v[196:199], v236, s[24:25] offset:2048 nt
	global_load_dwordx4 v[200:203], v236, s[24:25] offset:3072 nt

.Lrp00_same0:
	s_lshl_b32 s9, s6, 11
	s_add_u32 s9, s9, 0x30f8100
	s_add_u32 s34, s20, s9
	s_addc_u32 s35, s21, 0
	s_add_i32 s6, s6, 1
	s_cmp_lt_u32 s6, s7
	s_cbranch_scc0 .Lrp00_last0
	s_cmp_lt_u32 s6, 0x2000
	s_cselect_b32 s28, s16, s18
	s_cselect_b32 s29, s17, s19
	s_cselect_b32 s9, 0, 0x2000
	s_sub_u32 s9, s6, s9
	s_lshl_b32 s9, s9, 12
	s_add_u32 s28, s28, s9
	s_addc_u32 s29, s29, 0
	global_load_dwordx4 v[212:215], v236, s[28:29] offset:0 nt
	global_load_dwordx4 v[216:219], v236, s[28:29] offset:1024 nt
	global_load_dwordx4 v[220:223], v236, s[28:29] offset:2048 nt
	global_load_dwordx4 v[224:227], v236, s[28:29] offset:3072 nt
	s_waitcnt vmcnt(8)
	s_branch .Lrp00_go0

.Lrp00_same1:
	s_lshl_b32 s9, s6, 11
	s_add_u32 s9, s9, 0x30f8100
	s_add_u32 s34, s20, s9
	s_addc_u32 s35, s21, 0
	s_add_i32 s6, s6, 1
	s_cmp_lt_u32 s6, s7
	s_cbranch_scc0 .Lrp00_last1
	s_cmp_lt_u32 s6, 0x2000
	s_cselect_b32 s24, s16, s18
	s_cselect_b32 s25, s17, s19
	s_cselect_b32 s9, 0, 0x2000
	s_sub_u32 s9, s6, s9
	s_lshl_b32 s9, s9, 12
	s_add_u32 s24, s24, s9
	s_addc_u32 s25, s25, 0
	global_load_dwordx4 v[188:191], v236, s[24:25] offset:0 nt
	global_load_dwordx4 v[192:195], v236, s[24:25] offset:1024 nt
	global_load_dwordx4 v[196:199], v236, s[24:25] offset:2048 nt
	global_load_dwordx4 v[200:203], v236, s[24:25] offset:3072 nt
	s_waitcnt vmcnt(8)
	s_branch .Lrp00_go1

.Lxbi6_skip:
	s_barrier
	s_nop 0
	v_ashrrev_i32_e32 v1, 6, v0
	v_lshl_add_u32 v1, s0, 2, v1
	v_readlane_b32 s0, v241, 12
	s_nop 1
	v_mul_lo_u32 v28, v1, s0
	v_add_u32_e32 v1, s0, v28
	v_min_i32_e32 v31, 0x2800, v1
	v_cmp_lt_i32_e32 vcc, v28, v31
	s_and_saveexec_b64 s[0:1], vcc
	s_xor_b64 s[2:3], exec, s[0:1]
	s_cbranch_execz .LBB0_1149
	v_readfirstlane_b32 s6, v28
	v_readfirstlane_b32 s7, v31
	v_readlane_b32 s36, v242, 42
	v_readlane_b32 s37, v242, 43
	v_readlane_b32 s14, v242, 1
	v_readlane_b32 s15, v242, 2
	v_readlane_b32 s20, v242, 3
	v_readlane_b32 s21, v242, 4
	v_and_b32_e32 v236, 63, v137
	v_lshlrev_b32_e32 v237, 3, v236
	v_lshlrev_b32_e32 v236, 4, v236
	v_mov_b32_e32 v238, 0x358637bd
	s_sub_u32 s36, s36, 0x118
	s_subb_u32 s37, s37, 0
	s_load_dwordx2 s[10:11], s[36:37], 0x60
	s_load_dwordx2 s[12:13], s[36:37], 0x68
	s_load_dwordx4 s[16:19], s[36:37], 0x0
	s_add_u32 s22, s20, 0x2f90000
	s_addc_u32 s23, s21, 0
	s_mov_b32 s8, -1
	s_waitcnt lgkmcnt(0)
	s_cmp_lt_u32 s6, 0x2000
	s_cselect_b32 s24, s16, s18
	s_cselect_b32 s25, s17, s19
	s_cselect_b32 s9, 0, 0x2000
	s_sub_u32 s9, s6, s9
	s_lshl_b32 s9, s9, 12
	s_add_u32 s24, s24, s9
	s_addc_u32 s25, s25, 0
	s_lshl_b32 s9, s6, 11
	s_add_u32 s9, s9, 0x9278100
	s_add_u32 s26, s20, s9
	s_addc_u32 s27, s21, 0
	global_load_dwordx2 v[204:205], v237, s[26:27] offset:0 nt
	global_load_dwordx2 v[206:207], v237, s[26:27] offset:512 nt
	global_load_dwordx2 v[208:209], v237, s[26:27] offset:1024 nt
	global_load_dwordx2 v[210:211], v237, s[26:27] offset:1536 nt
	global_load_dwordx4 v[188:191], v236, s[24:25] offset:0 nt
	global_load_dwordx4 v[192:195], v236, s[24:25] offset:1024 nt
	global_load_dwordx4 v[196:199], v236, s[24:25] offset:2048 nt
	global_load_dwordx4 v[200:203], v236, s[24:25] offset:3072 nt

.Lrp10_same0:
	s_lshl_b32 s9, s6, 12
	s_add_u32 s32, s14, s9
	s_addc_u32 s33, s15, 0
	s_lshl_b32 s9, s6, 11
	s_add_u32 s9, s9, 0x30f8100
	s_add_u32 s34, s20, s9
	s_addc_u32 s35, s21, 0
	s_add_i32 s6, s6, 1
	s_cmp_lt_u32 s6, s7
	s_cbranch_scc0 .Lrp10_last0
	s_cmp_lt_u32 s6, 0x2000
	s_cselect_b32 s28, s16, s18
	s_cselect_b32 s29, s17, s19
	s_cselect_b32 s9, 0, 0x2000
	s_sub_u32 s9, s6, s9
	s_lshl_b32 s9, s9, 12
	s_add_u32 s28, s28, s9
	s_addc_u32 s29, s29, 0
	s_lshl_b32 s9, s6, 11
	s_add_u32 s9, s9, 0x9278100
	s_add_u32 s30, s20, s9
	s_addc_u32 s31, s21, 0
	global_load_dwordx2 v[228:229], v237, s[30:31] offset:0 nt
	global_load_dwordx2 v[230:231], v237, s[30:31] offset:512 nt
	global_load_dwordx2 v[232:233], v237, s[30:31] offset:1024 nt
	global_load_dwordx2 v[234:235], v237, s[30:31] offset:1536 nt
	global_load_dwordx4 v[212:215], v236, s[28:29] offset:0 nt
	global_load_dwordx4 v[216:219], v236, s[28:29] offset:1024 nt
	global_load_dwordx4 v[220:223], v236, s[28:29] offset:2048 nt
	global_load_dwordx4 v[224:227], v236, s[28:29] offset:3072 nt
	s_waitcnt vmcnt(16)
	s_branch .Lrp10_go0

.Lrp10_same1:
	s_lshl_b32 s9, s6, 12
	s_add_u32 s32, s14, s9
	s_addc_u32 s33, s15, 0
	s_lshl_b32 s9, s6, 11
	s_add_u32 s9, s9, 0x30f8100
	s_add_u32 s34, s20, s9
	s_addc_u32 s35, s21, 0
	s_add_i32 s6, s6, 1
	s_cmp_lt_u32 s6, s7
	s_cbranch_scc0 .Lrp10_last1
	s_cmp_lt_u32 s6, 0x2000
	s_cselect_b32 s24, s16, s18
	s_cselect_b32 s25, s17, s19
	s_cselect_b32 s9, 0, 0x2000
	s_sub_u32 s9, s6, s9
	s_lshl_b32 s9, s9, 12
	s_add_u32 s24, s24, s9
	s_addc_u32 s25, s25, 0
	s_lshl_b32 s9, s6, 11
	s_add_u32 s9, s9, 0x9278100
	s_add_u32 s26, s20, s9
	s_addc_u32 s27, s21, 0
	global_load_dwordx2 v[204:205], v237, s[26:27] offset:0 nt
	global_load_dwordx2 v[206:207], v237, s[26:27] offset:512 nt
	global_load_dwordx2 v[208:209], v237, s[26:27] offset:1024 nt
	global_load_dwordx2 v[210:211], v237, s[26:27] offset:1536 nt
	global_load_dwordx4 v[188:191], v236, s[24:25] offset:0 nt
	global_load_dwordx4 v[192:195], v236, s[24:25] offset:1024 nt
	global_load_dwordx4 v[196:199], v236, s[24:25] offset:2048 nt
	global_load_dwordx4 v[200:203], v236, s[24:25] offset:3072 nt
	s_waitcnt vmcnt(16)
	s_branch .Lrp10_go1

.Lxbi9_skip:
	s_barrier
	v_readfirstlane_b32 s4, v1
	s_mul_i32 s3, s3, s4
	s_mul_hi_u32 s3, s4, s3
	s_add_i32 s4, s4, s3
	s_mul_hi_u32 s3, s1, s4
	s_mul_i32 s4, s3, s0
	s_sub_i32 s1, s1, s4
	s_add_i32 s4, s3, 1
	s_sub_i32 s5, s1, s0
	s_cmp_ge_u32 s1, s0
	s_cselect_b32 s3, s4, s3
	s_cselect_b32 s1, s5, s1
	s_add_i32 s4, s3, 1
	s_cmp_ge_u32 s1, s0
	s_cselect_b32 s0, s4, s3
	s_xor_b32 s0, s0, s2
	s_sub_i32 s1, s0, s2
	v_ashrrev_i32_e32 v2, 6, v0
	v_readlane_b32 s0, v242, 0
	v_writelane_b32 v242, s1, 56
	s_nop 0
	v_lshl_add_u32 v1, s0, 2, v2
	v_mul_lo_u32 v28, v1, s1
	v_add_u32_e32 v1, s1, v28
	v_min_i32_e32 v90, 0x2800, v1
	v_cmp_lt_i32_e32 vcc, v28, v90
	s_and_saveexec_b64 s[0:1], vcc
	s_cbranch_execz .LBB0_1322
	v_readfirstlane_b32 s6, v28
	v_readfirstlane_b32 s7, v90
	v_readlane_b32 s36, v242, 42
	v_readlane_b32 s37, v242, 43
	v_readlane_b32 s14, v242, 1
	v_readlane_b32 s15, v242, 2
	v_readlane_b32 s20, v242, 3
	v_readlane_b32 s21, v242, 4
	v_and_b32_e32 v236, 63, v137
	v_lshlrev_b32_e32 v237, 3, v236
	v_lshlrev_b32_e32 v236, 4, v236
	v_mov_b32_e32 v238, 0x358637bd
	s_sub_u32 s36, s36, 0x118
	s_subb_u32 s37, s37, 0
	s_load_dwordx2 s[10:11], s[36:37], 0x70
	s_load_dwordx2 s[12:13], s[36:37], 0x58
	s_add_u32 s22, s20, 0x2f90000
	s_addc_u32 s23, s21, 0
	s_mov_b32 s8, -1
	s_waitcnt lgkmcnt(0)
	s_add_u32 s12, s12, 0x1000
	s_addc_u32 s13, s13, 0
	s_lshl_b32 s9, s6, 12
	s_add_u32 s24, s14, s9
	s_addc_u32 s25, s15, 0
	s_lshl_b32 s9, s6, 11
	s_add_u32 s9, s9, 0x9278100
	s_add_u32 s26, s20, s9
	s_addc_u32 s27, s21, 0
	global_load_dwordx2 v[204:205], v237, s[26:27] offset:0 nt
	global_load_dwordx2 v[206:207], v237, s[26:27] offset:512 nt
	global_load_dwordx2 v[208:209], v237, s[26:27] offset:1024 nt
	global_load_dwordx2 v[210:211], v237, s[26:27] offset:1536 nt
	global_load_dwordx4 v[188:191], v236, s[24:25] offset:0 nt
	global_load_dwordx4 v[192:195], v236, s[24:25] offset:1024 nt
	global_load_dwordx4 v[196:199], v236, s[24:25] offset:2048 nt
	global_load_dwordx4 v[200:203], v236, s[24:25] offset:3072 nt

.Lrp20_same0:
	s_lshl_b32 s9, s6, 12
	s_add_u32 s32, s14, s9
	s_addc_u32 s33, s15, 0
	s_lshl_b32 s9, s6, 11
	s_add_u32 s9, s9, 0x30f8100
	s_add_u32 s34, s20, s9
	s_addc_u32 s35, s21, 0
	s_add_i32 s6, s6, 1
	s_cmp_lt_u32 s6, s7
	s_cbranch_scc0 .Lrp20_last0
	s_lshl_b32 s9, s6, 12
	s_add_u32 s28, s14, s9
	s_addc_u32 s29, s15, 0
	s_lshl_b32 s9, s6, 11
	s_add_u32 s9, s9, 0x9278100
	s_add_u32 s30, s20, s9
	s_addc_u32 s31, s21, 0
	global_load_dwordx2 v[228:229], v237, s[30:31] offset:0 nt
	global_load_dwordx2 v[230:231], v237, s[30:31] offset:512 nt
	global_load_dwordx2 v[232:233], v237, s[30:31] offset:1024 nt
	global_load_dwordx2 v[234:235], v237, s[30:31] offset:1536 nt
	global_load_dwordx4 v[212:215], v236, s[28:29] offset:0 nt
	global_load_dwordx4 v[216:219], v236, s[28:29] offset:1024 nt
	global_load_dwordx4 v[220:223], v236, s[28:29] offset:2048 nt
	global_load_dwordx4 v[224:227], v236, s[28:29] offset:3072 nt
	s_waitcnt vmcnt(16)
	s_branch .Lrp20_go0

.Lrp20_same1:
	s_lshl_b32 s9, s6, 12
	s_add_u32 s32, s14, s9
	s_addc_u32 s33, s15, 0
	s_lshl_b32 s9, s6, 11
	s_add_u32 s9, s9, 0x30f8100
	s_add_u32 s34, s20, s9
	s_addc_u32 s35, s21, 0
	s_add_i32 s6, s6, 1
	s_cmp_lt_u32 s6, s7
	s_cbranch_scc0 .Lrp20_last1
	s_lshl_b32 s9, s6, 12
	s_add_u32 s24, s14, s9
	s_addc_u32 s25, s15, 0
	s_lshl_b32 s9, s6, 11
	s_add_u32 s9, s9, 0x9278100
	s_add_u32 s26, s20, s9
	s_addc_u32 s27, s21, 0
	global_load_dwordx2 v[204:205], v237, s[26:27] offset:0 nt
	global_load_dwordx2 v[206:207], v237, s[26:27] offset:512 nt
	global_load_dwordx2 v[208:209], v237, s[26:27] offset:1024 nt
	global_load_dwordx2 v[210:211], v237, s[26:27] offset:1536 nt
	global_load_dwordx4 v[188:191], v236, s[24:25] offset:0 nt
	global_load_dwordx4 v[192:195], v236, s[24:25] offset:1024 nt
	global_load_dwordx4 v[196:199], v236, s[24:25] offset:2048 nt
	global_load_dwordx4 v[200:203], v236, s[24:25] offset:3072 nt
	s_waitcnt vmcnt(16)
	s_branch .Lrp20_go1

.Lxbi15_skip:
	s_barrier
	v_readlane_b32 s0, v242, 0
	v_ashrrev_i32_e32 v1, 6, v0
	s_nop 0
	v_lshl_add_u32 v1, s0, 2, v1
	v_mul_lo_u32 v16, v1, s56
	v_add_u32_e32 v1, s56, v16
	v_min_i32_e32 v62, 0x2800, v1
	v_cmp_lt_i32_e32 vcc, v16, v62
	s_and_saveexec_b64 s[0:1], vcc
	s_xor_b64 s[0:1], exec, s[0:1]
	s_cbranch_execz .LBB0_2147
	v_readfirstlane_b32 s6, v16
	v_readfirstlane_b32 s7, v62
	v_readlane_b32 s36, v242, 42
	v_readlane_b32 s37, v242, 43
	v_readlane_b32 s14, v242, 1
	v_readlane_b32 s15, v242, 2
	v_readlane_b32 s20, v242, 3
	v_readlane_b32 s21, v242, 4
	v_and_b32_e32 v236, 63, v137
	v_lshlrev_b32_e32 v237, 3, v236
	v_lshlrev_b32_e32 v236, 4, v236
	v_mov_b32_e32 v238, 0x358637bd
	s_sub_u32 s36, s36, 0x118
	s_subb_u32 s37, s37, 0
	s_load_dwordx2 s[10:11], s[36:37], 0x60
	s_load_dwordx2 s[12:13], s[36:37], 0x68
	s_add_u32 s22, s20, 0x2f90000
	s_addc_u32 s23, s21, 0
	s_mov_b32 s8, -1
	s_waitcnt lgkmcnt(0)
	s_add_u32 s10, s10, 0x1000
	s_addc_u32 s11, s11, 0
	s_add_u32 s12, s12, 0x1000
	s_addc_u32 s13, s13, 0
	s_lshl_b32 s9, s6, 12
	s_add_u32 s24, s14, s9
	s_addc_u32 s25, s15, 0
	s_lshl_b32 s9, s6, 11
	s_add_u32 s9, s9, 0x9278100
	s_add_u32 s26, s20, s9
	s_addc_u32 s27, s21, 0
	global_load_dwordx2 v[204:205], v237, s[26:27] offset:0 nt
	global_load_dwordx2 v[206:207], v237, s[26:27] offset:512 nt
	global_load_dwordx2 v[208:209], v237, s[26:27] offset:1024 nt
	global_load_dwordx2 v[210:211], v237, s[26:27] offset:1536 nt
	global_load_dwordx4 v[188:191], v236, s[24:25] offset:0 nt
	global_load_dwordx4 v[192:195], v236, s[24:25] offset:1024 nt
	global_load_dwordx4 v[196:199], v236, s[24:25] offset:2048 nt
	global_load_dwordx4 v[200:203], v236, s[24:25] offset:3072 nt

.Lxbi18_skip:
	s_barrier
	v_readlane_b32 s0, v242, 0
	v_ashrrev_i32_e32 v0, 6, v137
	s_nop 0
	v_lshl_add_u32 v0, s0, 2, v0
	v_mul_lo_u32 v0, v0, s56
	v_add_u32_e32 v1, s56, v0
	v_min_i32_e32 v26, 0x2800, v1
	v_cmp_lt_i32_e32 vcc, v0, v26
	s_and_saveexec_b64 s[0:1], vcc
	s_cbranch_execz .LBB0_2320
	v_readfirstlane_b32 s6, v0
	v_readfirstlane_b32 s7, v26
	v_readlane_b32 s36, v242, 42
	v_readlane_b32 s37, v242, 43
	v_readlane_b32 s14, v242, 1
	v_readlane_b32 s15, v242, 2
	v_readlane_b32 s20, v242, 3
	v_readlane_b32 s21, v242, 4
	v_and_b32_e32 v236, 63, v137
	v_lshlrev_b32_e32 v237, 3, v236
	v_lshlrev_b32_e32 v236, 4, v236
	v_mov_b32_e32 v238, 0x358637bd
	s_sub_u32 s36, s36, 0x118
	s_subb_u32 s37, s37, 0
	s_load_dwordx2 s[10:11], s[36:37], 0x70
	s_add_u32 s22, s20, 0x2f90000
	s_addc_u32 s23, s21, 0
	s_mov_b32 s8, -1
	s_waitcnt lgkmcnt(0)
	s_add_u32 s10, s10, 0x1000
	s_addc_u32 s11, s11, 0
	s_lshl_b32 s9, s6, 12
	s_add_u32 s24, s14, s9
	s_addc_u32 s25, s15, 0
	s_lshl_b32 s9, s6, 11
	s_add_u32 s9, s9, 0x9278100
	s_add_u32 s26, s20, s9
	s_addc_u32 s27, s21, 0
	global_load_dwordx2 v[204:205], v237, s[26:27] offset:0 nt
	global_load_dwordx2 v[206:207], v237, s[26:27] offset:512 nt
	global_load_dwordx2 v[208:209], v237, s[26:27] offset:1024 nt
	global_load_dwordx2 v[210:211], v237, s[26:27] offset:1536 nt
	global_load_dwordx4 v[188:191], v236, s[24:25] offset:0 nt
	global_load_dwordx4 v[192:195], v236, s[24:25] offset:1024 nt
	global_load_dwordx4 v[196:199], v236, s[24:25] offset:2048 nt
	global_load_dwordx4 v[200:203], v236, s[24:25] offset:3072 nt

.Lrp21_same0:
	s_lshl_b32 s9, s6, 12
	s_add_u32 s32, s14, s9
	s_addc_u32 s33, s15, 0
	s_add_i32 s6, s6, 1
	s_cmp_lt_u32 s6, s7
	s_cbranch_scc0 .Lrp21_last0
	s_lshl_b32 s9, s6, 12
	s_add_u32 s28, s14, s9
	s_addc_u32 s29, s15, 0
	s_lshl_b32 s9, s6, 11
	s_add_u32 s9, s9, 0x9278100
	s_add_u32 s30, s20, s9
	s_addc_u32 s31, s21, 0
	global_load_dwordx2 v[228:229], v237, s[30:31] offset:0 nt
	global_load_dwordx2 v[230:231], v237, s[30:31] offset:512 nt
	global_load_dwordx2 v[232:233], v237, s[30:31] offset:1024 nt
	global_load_dwordx2 v[234:235], v237, s[30:31] offset:1536 nt
	global_load_dwordx4 v[212:215], v236, s[28:29] offset:0 nt
	global_load_dwordx4 v[216:219], v236, s[28:29] offset:1024 nt
	global_load_dwordx4 v[220:223], v236, s[28:29] offset:2048 nt
	global_load_dwordx4 v[224:227], v236, s[28:29] offset:3072 nt
	s_waitcnt vmcnt(12)
	s_branch .Lrp21_go0

.Lrp21_same1:
	s_lshl_b32 s9, s6, 12
	s_add_u32 s32, s14, s9
	s_addc_u32 s33, s15, 0
	s_add_i32 s6, s6, 1
	s_cmp_lt_u32 s6, s7
	s_cbranch_scc0 .Lrp21_last1
	s_lshl_b32 s9, s6, 12
	s_add_u32 s24, s14, s9
	s_addc_u32 s25, s15, 0
	s_lshl_b32 s9, s6, 11
	s_add_u32 s9, s9, 0x9278100
	s_add_u32 s26, s20, s9
	s_addc_u32 s27, s21, 0
	global_load_dwordx2 v[204:205], v237, s[26:27] offset:0 nt
	global_load_dwordx2 v[206:207], v237, s[26:27] offset:512 nt
	global_load_dwordx2 v[208:209], v237, s[26:27] offset:1024 nt
	global_load_dwordx2 v[210:211], v237, s[26:27] offset:1536 nt
	global_load_dwordx4 v[188:191], v236, s[24:25] offset:0 nt
	global_load_dwordx4 v[192:195], v236, s[24:25] offset:1024 nt
	global_load_dwordx4 v[196:199], v236, s[24:25] offset:2048 nt
	global_load_dwordx4 v[200:203], v236, s[24:25] offset:3072 nt
	s_waitcnt vmcnt(12)
	s_branch .Lrp21_go1
